# stack6 + GEMM K-loop LDS-DMA loads in SADDR form (no per-load 64-bit VALU address adds)
# speedup vs baseline: 1.0074x; 1.0074x over previous
.LBB0_290:
	s_add_i32 s29, s30, 2
	s_add_u32 s31, s56, 0x80
	s_addc_u32 s35, s57, 0
	s_add_i32 s72, 0, 0x10000
	s_cmp_eq_u32 s67, s30
	s_cselect_b32 s55, s1, s35
	s_cselect_b32 s54, s0, s31
	v_add_u32_e32 v144, s72, v147
	s_cselect_b32 s31, s53, s19
	s_cselect_b32 s30, s52, s18
	s_add_i32 s35, 0, 0x14000
	ds_read_b128 v[140:143], v144
	ds_read_b128 v[176:179], v144 offset:1024
	ds_read_b128 v[180:183], v144 offset:2048
	ds_read_b128 v[184:187], v144 offset:3072
	v_add_u32_e32 v144, s35, v147
	ds_read_b128 v[188:191], v144
	ds_read_b128 v[192:195], v144 offset:1024
	ds_read_b128 v[196:199], v144 offset:2048
	ds_read_b128 v[200:203], v144 offset:3072
	s_add_i32 m0, s58, 0xc000
	ds_read_b128 v[204:207], v169
	ds_read_b128 v[208:211], v169 offset:1024
	ds_read_b128 v[212:215], v169 offset:2048
	ds_read_b128 v[216:219], v169 offset:3072
	ds_read_b128 v[220:223], v169 offset:4096
	ds_read_b128 v[224:227], v169 offset:5120
	ds_read_b128 v[228:231], v169 offset:6144
	ds_read_b128 v[232:235], v169 offset:7168
	global_load_lds_dwordx4 v136, s[56:57]
	s_add_i32 m0, s58, 0xe000
	s_nop 0
	global_load_lds_dwordx4 v138, s[56:57]
	s_waitcnt vmcnt(8)
	s_waitcnt lgkmcnt(0)
	s_barrier
	s_waitcnt lgkmcnt(0)
	v_mfma_f32_16x16x32_bf16 v[126:129], v[140:143], v[204:207], v[126:129]
	v_mfma_f32_16x16x32_bf16 v[114:117], v[180:183], v[204:207], v[114:117]
	v_mfma_f32_16x16x32_bf16 v[106:109], v[140:143], v[212:215], v[106:109]
	v_mfma_f32_16x16x32_bf16 v[98:101], v[180:183], v[212:215], v[98:101]
	v_mfma_f32_16x16x32_bf16 v[90:93], v[140:143], v[220:223], v[90:93]
	v_mfma_f32_16x16x32_bf16 v[82:85], v[180:183], v[220:223], v[82:85]
	v_mfma_f32_16x16x32_bf16 v[74:77], v[140:143], v[228:231], v[74:77]
	v_mfma_f32_16x16x32_bf16 v[54:57], v[180:183], v[228:231], v[54:57]
	v_mfma_f32_16x16x32_bf16 v[126:129], v[176:179], v[208:211], v[126:129]
	v_mfma_f32_16x16x32_bf16 v[114:117], v[184:187], v[208:211], v[114:117]
	v_mfma_f32_16x16x32_bf16 v[106:109], v[176:179], v[216:219], v[106:109]
	v_mfma_f32_16x16x32_bf16 v[98:101], v[184:187], v[216:219], v[98:101]
	v_mfma_f32_16x16x32_bf16 v[90:93], v[176:179], v[224:227], v[90:93]
	v_mfma_f32_16x16x32_bf16 v[82:85], v[184:187], v[224:227], v[82:85]
	v_mfma_f32_16x16x32_bf16 v[74:77], v[176:179], v[232:235], v[74:77]
	v_mfma_f32_16x16x32_bf16 v[54:57], v[184:187], v[232:235], v[54:57]
	v_mfma_f32_16x16x32_bf16 v[118:121], v[188:191], v[204:207], v[118:121]
	v_mfma_f32_16x16x32_bf16 v[122:125], v[196:199], v[204:207], v[122:125]
	v_mfma_f32_16x16x32_bf16 v[102:105], v[188:191], v[212:215], v[102:105]
	v_mfma_f32_16x16x32_bf16 v[110:113], v[196:199], v[212:215], v[110:113]
	v_mfma_f32_16x16x32_bf16 v[86:89], v[188:191], v[220:223], v[86:89]
	v_mfma_f32_16x16x32_bf16 v[94:97], v[196:199], v[220:223], v[94:97]
	v_mfma_f32_16x16x32_bf16 v[70:73], v[188:191], v[228:231], v[70:73]
	v_mfma_f32_16x16x32_bf16 v[78:81], v[196:199], v[228:231], v[78:81]
	v_mfma_f32_16x16x32_bf16 v[118:121], v[192:195], v[208:211], v[118:121]
	v_mfma_f32_16x16x32_bf16 v[122:125], v[200:203], v[208:211], v[122:125]
	v_mfma_f32_16x16x32_bf16 v[102:105], v[192:195], v[216:219], v[102:105]
	v_mfma_f32_16x16x32_bf16 v[110:113], v[200:203], v[216:219], v[110:113]
	v_mfma_f32_16x16x32_bf16 v[86:89], v[192:195], v[224:227], v[86:89]
	v_mfma_f32_16x16x32_bf16 v[94:97], v[200:203], v[224:227], v[94:97]
	v_mfma_f32_16x16x32_bf16 v[70:73], v[192:195], v[232:235], v[70:73]
	v_mfma_f32_16x16x32_bf16 v[78:81], v[200:203], v[232:235], v[78:81]
	s_barrier
	s_add_i32 s72, s72, s23
	s_mov_b32 m0, s72
	ds_read_b128 v[204:207], v169 offset:16384
	ds_read_b128 v[208:211], v169 offset:17408
	ds_read_b128 v[212:215], v169 offset:18432
	ds_read_b128 v[216:219], v169 offset:19456
	ds_read_b128 v[220:223], v169 offset:20480
	ds_read_b128 v[224:227], v169 offset:21504
	ds_read_b128 v[228:231], v169 offset:22528
	ds_read_b128 v[232:235], v169 offset:23552
	global_load_lds_dwordx4 v0, s[30:31]
	s_add_i32 m0, s72, 0x2000
	s_nop 0
	global_load_lds_dwordx4 v134, s[30:31]
	s_add_u32 s30, s30, s80
	s_addc_u32 s31, s31, 0
	s_add_i32 s35, s35, s23
	s_mov_b32 m0, s35
	s_nop 0
	global_load_lds_dwordx4 v0, s[30:31]
	s_add_i32 m0, s35, 0x2000
	s_nop 0
	global_load_lds_dwordx4 v134, s[30:31]
	s_mov_b32 m0, s58
	s_nop 0
	global_load_lds_dwordx4 v130, s[54:55]
	s_mov_b32 m0, s59
	s_nop 0
	global_load_lds_dwordx4 v132, s[54:55]
	s_sub_u32 s100, s30, s80
	s_subb_u32 s101, s31, 0
	s_add_u32 s100, s100, s94
	s_addc_u32 s101, s101, s95
	s_add_u32 vcc_lo, s54, s94
	s_addc_u32 vcc_hi, s55, s95
	s_waitcnt vmcnt(8)
	s_waitcnt lgkmcnt(0)
	s_barrier
	s_waitcnt lgkmcnt(0)
	v_mfma_f32_16x16x32_bf16 v[58:61], v[140:143], v[204:207], v[58:61]
	v_mfma_f32_16x16x32_bf16 v[62:65], v[180:183], v[204:207], v[62:65]
	v_mfma_f32_16x16x32_bf16 v[38:41], v[140:143], v[212:215], v[38:41]
	v_mfma_f32_16x16x32_bf16 v[42:45], v[180:183], v[212:215], v[42:45]
	v_mfma_f32_16x16x32_bf16 v[18:21], v[140:143], v[220:223], v[18:21]
	v_mfma_f32_16x16x32_bf16 v[26:29], v[180:183], v[220:223], v[26:29]
	v_mfma_f32_16x16x32_bf16 v[2:5], v[140:143], v[228:231], v[2:5]
	v_mfma_f32_16x16x32_bf16 v[6:9], v[180:183], v[228:231], v[6:9]
	v_mfma_f32_16x16x32_bf16 v[58:61], v[176:179], v[208:211], v[58:61]
	v_mfma_f32_16x16x32_bf16 v[62:65], v[184:187], v[208:211], v[62:65]
	v_mfma_f32_16x16x32_bf16 v[38:41], v[176:179], v[216:219], v[38:41]
	v_mfma_f32_16x16x32_bf16 v[42:45], v[184:187], v[216:219], v[42:45]
	v_mfma_f32_16x16x32_bf16 v[18:21], v[176:179], v[224:227], v[18:21]
	v_mfma_f32_16x16x32_bf16 v[26:29], v[184:187], v[224:227], v[26:29]
	v_mfma_f32_16x16x32_bf16 v[2:5], v[176:179], v[232:235], v[2:5]
	v_mfma_f32_16x16x32_bf16 v[6:9], v[184:187], v[232:235], v[6:9]
	v_mfma_f32_16x16x32_bf16 v[50:53], v[188:191], v[204:207], v[50:53]
	v_mfma_f32_16x16x32_bf16 v[66:69], v[196:199], v[204:207], v[66:69]
	v_mfma_f32_16x16x32_bf16 v[34:37], v[188:191], v[212:215], v[34:37]
	v_mfma_f32_16x16x32_bf16 v[46:49], v[196:199], v[212:215], v[46:49]
	v_mfma_f32_16x16x32_bf16 v[14:17], v[188:191], v[220:223], v[14:17]
	v_mfma_f32_16x16x32_bf16 v[30:33], v[196:199], v[220:223], v[30:33]
	v_mfma_f32_16x16x32_bf16 v[10:13], v[188:191], v[228:231], v[10:13]
	v_mfma_f32_16x16x32_bf16 v[22:25], v[196:199], v[228:231], v[22:25]
	v_mfma_f32_16x16x32_bf16 v[50:53], v[192:195], v[208:211], v[50:53]
	v_mfma_f32_16x16x32_bf16 v[66:69], v[200:203], v[208:211], v[66:69]
	v_mfma_f32_16x16x32_bf16 v[34:37], v[192:195], v[216:219], v[34:37]
	v_mfma_f32_16x16x32_bf16 v[46:49], v[200:203], v[216:219], v[46:49]
	v_mfma_f32_16x16x32_bf16 v[14:17], v[192:195], v[224:227], v[14:17]
	v_mfma_f32_16x16x32_bf16 v[30:33], v[200:203], v[224:227], v[30:33]
	v_mfma_f32_16x16x32_bf16 v[10:13], v[192:195], v[232:235], v[10:13]
	v_mfma_f32_16x16x32_bf16 v[22:25], v[200:203], v[232:235], v[22:25]
	s_barrier
	s_add_i32 s35, 0, 0x18000
	s_add_i32 s72, 0, 0x1c000
	v_add_u32_e32 v184, s35, v147
	v_add_u32_e32 v200, s72, v147
	ds_read_b128 v[140:143], v184
	ds_read_b128 v[176:179], v184 offset:1024
	ds_read_b128 v[180:183], v184 offset:2048
	ds_read_b128 v[184:187], v184 offset:3072
	ds_read_b128 v[188:191], v200
	ds_read_b128 v[192:195], v200 offset:1024
	ds_read_b128 v[196:199], v200 offset:2048
	ds_read_b128 v[200:203], v200 offset:3072
	s_add_u32 s30, s54, s80
	s_addc_u32 s31, s55, 0
	s_mov_b32 m0, s60
	ds_read_b128 v[204:207], v169 offset:32768
	ds_read_b128 v[208:211], v169 offset:33792
	ds_read_b128 v[212:215], v169 offset:34816
	ds_read_b128 v[216:219], v169 offset:35840
	ds_read_b128 v[220:223], v169 offset:36864
	ds_read_b128 v[224:227], v169 offset:37888
	ds_read_b128 v[228:231], v169 offset:38912
	ds_read_b128 v[232:235], v169 offset:39936
	global_load_lds_dwordx4 v130, s[30:31]
	s_mov_b32 m0, s61
	s_nop 0
	global_load_lds_dwordx4 v132, s[30:31]
	s_waitcnt vmcnt(8)
	s_waitcnt lgkmcnt(0)
	s_barrier
	s_waitcnt lgkmcnt(0)
	v_mfma_f32_16x16x32_bf16 v[126:129], v[140:143], v[204:207], v[126:129]
	v_mfma_f32_16x16x32_bf16 v[114:117], v[180:183], v[204:207], v[114:117]
	v_mfma_f32_16x16x32_bf16 v[106:109], v[140:143], v[212:215], v[106:109]
	v_mfma_f32_16x16x32_bf16 v[98:101], v[180:183], v[212:215], v[98:101]
	v_mfma_f32_16x16x32_bf16 v[90:93], v[140:143], v[220:223], v[90:93]
	v_mfma_f32_16x16x32_bf16 v[82:85], v[180:183], v[220:223], v[82:85]
	v_mfma_f32_16x16x32_bf16 v[74:77], v[140:143], v[228:231], v[74:77]
	v_mfma_f32_16x16x32_bf16 v[54:57], v[180:183], v[228:231], v[54:57]
	v_mfma_f32_16x16x32_bf16 v[126:129], v[176:179], v[208:211], v[126:129]
	v_mfma_f32_16x16x32_bf16 v[114:117], v[184:187], v[208:211], v[114:117]
	v_mfma_f32_16x16x32_bf16 v[106:109], v[176:179], v[216:219], v[106:109]
	v_mfma_f32_16x16x32_bf16 v[98:101], v[184:187], v[216:219], v[98:101]
	v_mfma_f32_16x16x32_bf16 v[90:93], v[176:179], v[224:227], v[90:93]
	v_mfma_f32_16x16x32_bf16 v[82:85], v[184:187], v[224:227], v[82:85]
	v_mfma_f32_16x16x32_bf16 v[74:77], v[176:179], v[232:235], v[74:77]
	v_mfma_f32_16x16x32_bf16 v[54:57], v[184:187], v[232:235], v[54:57]
	v_mfma_f32_16x16x32_bf16 v[118:121], v[188:191], v[204:207], v[118:121]
	v_mfma_f32_16x16x32_bf16 v[122:125], v[196:199], v[204:207], v[122:125]
	v_mfma_f32_16x16x32_bf16 v[102:105], v[188:191], v[212:215], v[102:105]
	v_mfma_f32_16x16x32_bf16 v[110:113], v[196:199], v[212:215], v[110:113]
	v_mfma_f32_16x16x32_bf16 v[86:89], v[188:191], v[220:223], v[86:89]
	v_mfma_f32_16x16x32_bf16 v[94:97], v[196:199], v[220:223], v[94:97]
	v_mfma_f32_16x16x32_bf16 v[70:73], v[188:191], v[228:231], v[70:73]
	v_mfma_f32_16x16x32_bf16 v[78:81], v[196:199], v[228:231], v[78:81]
	v_mfma_f32_16x16x32_bf16 v[118:121], v[192:195], v[208:211], v[118:121]
	v_mfma_f32_16x16x32_bf16 v[122:125], v[200:203], v[208:211], v[122:125]
	v_mfma_f32_16x16x32_bf16 v[102:105], v[192:195], v[216:219], v[102:105]
	v_mfma_f32_16x16x32_bf16 v[110:113], v[200:203], v[216:219], v[110:113]
	v_mfma_f32_16x16x32_bf16 v[86:89], v[192:195], v[224:227], v[86:89]
	v_mfma_f32_16x16x32_bf16 v[94:97], v[200:203], v[224:227], v[94:97]
	v_mfma_f32_16x16x32_bf16 v[70:73], v[192:195], v[232:235], v[70:73]
	v_mfma_f32_16x16x32_bf16 v[78:81], v[200:203], v[232:235], v[78:81]
	s_barrier
	s_add_i32 s30, s35, s23
	s_mov_b32 m0, s30
	ds_read_b128 v[204:207], v169 offset:49152
	ds_read_b128 v[208:211], v169 offset:50176
	ds_read_b128 v[212:215], v169 offset:51200
	ds_read_b128 v[216:219], v169 offset:52224
	ds_read_b128 v[220:223], v169 offset:53248
	ds_read_b128 v[224:227], v169 offset:54272
	ds_read_b128 v[228:231], v169 offset:55296
	ds_read_b128 v[232:235], v169 offset:56320
	global_load_lds_dwordx4 v0, s[100:101]
	s_add_i32 m0, s30, 0x2000
	s_add_i32 s30, s72, s23
	global_load_lds_dwordx4 v134, s[100:101]
	s_add_u32 s100, s100, s80
	s_addc_u32 s101, s101, 0
	s_mov_b32 m0, s30
	s_nop 0
	global_load_lds_dwordx4 v0, s[100:101]
	s_add_i32 m0, s30, 0x2000
	s_nop 0
	global_load_lds_dwordx4 v134, s[100:101]
	s_mov_b32 m0, s64
	s_nop 0
	global_load_lds_dwordx4 v130, vcc
	s_mov_b32 m0, s65
	s_nop 0
	global_load_lds_dwordx4 v132, vcc
	s_waitcnt vmcnt(8)
	s_waitcnt lgkmcnt(0)
	s_barrier
	s_waitcnt lgkmcnt(0)
	v_mfma_f32_16x16x32_bf16 v[58:61], v[140:143], v[204:207], v[58:61]
	v_mfma_f32_16x16x32_bf16 v[62:65], v[180:183], v[204:207], v[62:65]
	v_mfma_f32_16x16x32_bf16 v[38:41], v[140:143], v[212:215], v[38:41]
	v_mfma_f32_16x16x32_bf16 v[42:45], v[180:183], v[212:215], v[42:45]
	v_mfma_f32_16x16x32_bf16 v[18:21], v[140:143], v[220:223], v[18:21]
	v_mfma_f32_16x16x32_bf16 v[26:29], v[180:183], v[220:223], v[26:29]
	v_mfma_f32_16x16x32_bf16 v[2:5], v[140:143], v[228:231], v[2:5]
	v_mfma_f32_16x16x32_bf16 v[6:9], v[180:183], v[228:231], v[6:9]
	v_mfma_f32_16x16x32_bf16 v[58:61], v[176:179], v[208:211], v[58:61]
	v_mfma_f32_16x16x32_bf16 v[62:65], v[184:187], v[208:211], v[62:65]
	v_mfma_f32_16x16x32_bf16 v[38:41], v[176:179], v[216:219], v[38:41]
	v_mfma_f32_16x16x32_bf16 v[42:45], v[184:187], v[216:219], v[42:45]
	v_mfma_f32_16x16x32_bf16 v[18:21], v[176:179], v[224:227], v[18:21]
	v_mfma_f32_16x16x32_bf16 v[26:29], v[184:187], v[224:227], v[26:29]
	v_mfma_f32_16x16x32_bf16 v[2:5], v[176:179], v[232:235], v[2:5]
	v_mfma_f32_16x16x32_bf16 v[6:9], v[184:187], v[232:235], v[6:9]
	v_mfma_f32_16x16x32_bf16 v[50:53], v[188:191], v[204:207], v[50:53]
	v_mfma_f32_16x16x32_bf16 v[66:69], v[196:199], v[204:207], v[66:69]
	v_mfma_f32_16x16x32_bf16 v[34:37], v[188:191], v[212:215], v[34:37]
	v_mfma_f32_16x16x32_bf16 v[46:49], v[196:199], v[212:215], v[46:49]
	v_mfma_f32_16x16x32_bf16 v[14:17], v[188:191], v[220:223], v[14:17]
	v_mfma_f32_16x16x32_bf16 v[30:33], v[196:199], v[220:223], v[30:33]
	v_mfma_f32_16x16x32_bf16 v[10:13], v[188:191], v[228:231], v[10:13]
	v_mfma_f32_16x16x32_bf16 v[22:25], v[196:199], v[228:231], v[22:25]
	v_mfma_f32_16x16x32_bf16 v[50:53], v[192:195], v[208:211], v[50:53]
	v_mfma_f32_16x16x32_bf16 v[66:69], v[200:203], v[208:211], v[66:69]
	v_mfma_f32_16x16x32_bf16 v[34:37], v[192:195], v[216:219], v[34:37]
	v_mfma_f32_16x16x32_bf16 v[46:49], v[200:203], v[216:219], v[46:49]
	v_mfma_f32_16x16x32_bf16 v[14:17], v[192:195], v[224:227], v[14:17]
	v_mfma_f32_16x16x32_bf16 v[30:33], v[200:203], v[224:227], v[30:33]
	v_mfma_f32_16x16x32_bf16 v[10:13], v[192:195], v[232:235], v[10:13]
	v_mfma_f32_16x16x32_bf16 v[22:25], v[200:203], v[232:235], v[22:25]
	s_barrier
	s_add_u32 s56, s56, 0x100
	s_addc_u32 s57, s57, 0
	s_add_u32 s18, s18, 0x100
	s_addc_u32 s19, s19, 0
	s_cmp_ge_u32 s29, s66
	s_mov_b32 s30, s29
	s_cbranch_scc0 .LBB0_290
	s_and_b64 vcc, exec, s[20:21]
	s_cbranch_vccz .LBB0_293
	s_barrier

.LBB0_334:
	s_add_i32 s66, s20, 2
	s_add_u32 s67, s16, 0x80
	s_addc_u32 s21, s17, 0
	s_add_i32 s72, 0, 0x10000
	s_cmp_eq_u32 s58, s20
	s_cselect_b32 s21, s1, s21
	s_cselect_b32 s20, s0, s67
	v_add_u32_e32 v140, s72, v143
	s_cselect_b32 s71, s15, s65
	s_cselect_b32 s70, s14, s64
	s_add_i32 s67, 0, 0x14000
	ds_read_b128 v[160:163], v140
	ds_read_b128 v[164:167], v140 offset:1024
	ds_read_b128 v[168:171], v140 offset:2048
	ds_read_b128 v[172:175], v140 offset:3072
	v_add_u32_e32 v140, s67, v143
	ds_read_b128 v[176:179], v140
	ds_read_b128 v[180:183], v140 offset:1024
	ds_read_b128 v[184:187], v140 offset:2048
	ds_read_b128 v[188:191], v140 offset:3072
	s_add_i32 m0, s19, 0xc000
	ds_read_b128 v[192:195], v146
	ds_read_b128 v[196:199], v146 offset:1024
	ds_read_b128 v[200:203], v146 offset:2048
	ds_read_b128 v[204:207], v146 offset:3072
	ds_read_b128 v[208:211], v146 offset:4096
	ds_read_b128 v[212:215], v146 offset:5120
	ds_read_b128 v[216:219], v146 offset:6144
	ds_read_b128 v[220:223], v146 offset:7168
	global_load_lds_dwordx4 v136, s[16:17]
	s_add_i32 m0, s19, 0xe000
	s_nop 0
	global_load_lds_dwordx4 v138, s[16:17]
	s_waitcnt vmcnt(8)
	s_waitcnt lgkmcnt(0)
	s_barrier
	s_waitcnt lgkmcnt(0)
	v_mfma_f32_16x16x32_bf16 v[126:129], v[160:163], v[192:195], v[126:129]
	v_mfma_f32_16x16x32_bf16 v[122:125], v[168:171], v[192:195], v[122:125]
	v_mfma_f32_16x16x32_bf16 v[110:113], v[160:163], v[200:203], v[110:113]
	v_mfma_f32_16x16x32_bf16 v[106:109], v[168:171], v[200:203], v[106:109]
	v_mfma_f32_16x16x32_bf16 v[94:97], v[160:163], v[208:211], v[94:97]
	v_mfma_f32_16x16x32_bf16 v[90:93], v[168:171], v[208:211], v[90:93]
	v_mfma_f32_16x16x32_bf16 v[78:81], v[160:163], v[216:219], v[78:81]
	v_mfma_f32_16x16x32_bf16 v[74:77], v[168:171], v[216:219], v[74:77]
	v_mfma_f32_16x16x32_bf16 v[126:129], v[164:167], v[196:199], v[126:129]
	v_mfma_f32_16x16x32_bf16 v[122:125], v[172:175], v[196:199], v[122:125]
	v_mfma_f32_16x16x32_bf16 v[110:113], v[164:167], v[204:207], v[110:113]
	v_mfma_f32_16x16x32_bf16 v[106:109], v[172:175], v[204:207], v[106:109]
	v_mfma_f32_16x16x32_bf16 v[94:97], v[164:167], v[212:215], v[94:97]
	v_mfma_f32_16x16x32_bf16 v[90:93], v[172:175], v[212:215], v[90:93]
	v_mfma_f32_16x16x32_bf16 v[78:81], v[164:167], v[220:223], v[78:81]
	v_mfma_f32_16x16x32_bf16 v[74:77], v[172:175], v[220:223], v[74:77]
	v_mfma_f32_16x16x32_bf16 v[118:121], v[176:179], v[192:195], v[118:121]
	v_mfma_f32_16x16x32_bf16 v[114:117], v[184:187], v[192:195], v[114:117]
	v_mfma_f32_16x16x32_bf16 v[102:105], v[176:179], v[200:203], v[102:105]
	v_mfma_f32_16x16x32_bf16 v[98:101], v[184:187], v[200:203], v[98:101]
	v_mfma_f32_16x16x32_bf16 v[86:89], v[176:179], v[208:211], v[86:89]
	v_mfma_f32_16x16x32_bf16 v[82:85], v[184:187], v[208:211], v[82:85]
	v_mfma_f32_16x16x32_bf16 v[70:73], v[176:179], v[216:219], v[70:73]
	v_mfma_f32_16x16x32_bf16 v[66:69], v[184:187], v[216:219], v[66:69]
	v_mfma_f32_16x16x32_bf16 v[118:121], v[180:183], v[196:199], v[118:121]
	v_mfma_f32_16x16x32_bf16 v[114:117], v[188:191], v[196:199], v[114:117]
	v_mfma_f32_16x16x32_bf16 v[102:105], v[180:183], v[204:207], v[102:105]
	v_mfma_f32_16x16x32_bf16 v[98:101], v[188:191], v[204:207], v[98:101]
	v_mfma_f32_16x16x32_bf16 v[86:89], v[180:183], v[212:215], v[86:89]
	v_mfma_f32_16x16x32_bf16 v[82:85], v[188:191], v[212:215], v[82:85]
	v_mfma_f32_16x16x32_bf16 v[70:73], v[180:183], v[220:223], v[70:73]
	v_mfma_f32_16x16x32_bf16 v[66:69], v[188:191], v[220:223], v[66:69]
	s_barrier
	s_add_i32 s72, s72, s35
	s_mov_b32 m0, s72
	ds_read_b128 v[192:195], v146 offset:16384
	ds_read_b128 v[196:199], v146 offset:17408
	ds_read_b128 v[200:203], v146 offset:18432
	ds_read_b128 v[204:207], v146 offset:19456
	ds_read_b128 v[208:211], v146 offset:20480
	ds_read_b128 v[212:215], v146 offset:21504
	ds_read_b128 v[216:219], v146 offset:22528
	ds_read_b128 v[220:223], v146 offset:23552
	global_load_lds_dwordx4 v0, s[70:71]
	s_add_i32 m0, s72, 0x2000
	s_nop 0
	global_load_lds_dwordx4 v134, s[70:71]
	s_add_u32 s70, s70, s80
	s_addc_u32 s71, s71, 0
	s_add_i32 s67, s67, s35
	s_mov_b32 m0, s67
	s_nop 0
	global_load_lds_dwordx4 v0, s[70:71]
	s_add_i32 m0, s67, 0x2000
	s_nop 0
	global_load_lds_dwordx4 v134, s[70:71]
	s_mov_b32 m0, s19
	s_nop 0
	global_load_lds_dwordx4 v130, s[20:21]
	s_mov_b32 m0, s29
	s_nop 0
	global_load_lds_dwordx4 v132, s[20:21]
	s_sub_u32 s100, s70, s80
	s_subb_u32 s101, s71, 0
	s_add_u32 s100, s100, s94
	s_addc_u32 s101, s101, s95
	s_add_u32 vcc_lo, s20, s94
	s_addc_u32 vcc_hi, s21, s95
	s_waitcnt vmcnt(8)
	s_waitcnt lgkmcnt(0)
	s_barrier
	s_waitcnt lgkmcnt(0)
	v_mfma_f32_16x16x32_bf16 v[62:65], v[160:163], v[192:195], v[62:65]
	v_mfma_f32_16x16x32_bf16 v[58:61], v[168:171], v[192:195], v[58:61]
	v_mfma_f32_16x16x32_bf16 v[46:49], v[160:163], v[200:203], v[46:49]
	v_mfma_f32_16x16x32_bf16 v[42:45], v[168:171], v[200:203], v[42:45]
	v_mfma_f32_16x16x32_bf16 v[30:33], v[160:163], v[208:211], v[30:33]
	v_mfma_f32_16x16x32_bf16 v[26:29], v[168:171], v[208:211], v[26:29]
	v_mfma_f32_16x16x32_bf16 v[14:17], v[160:163], v[216:219], v[14:17]
	v_mfma_f32_16x16x32_bf16 v[10:13], v[168:171], v[216:219], v[10:13]
	v_mfma_f32_16x16x32_bf16 v[62:65], v[164:167], v[196:199], v[62:65]
	v_mfma_f32_16x16x32_bf16 v[58:61], v[172:175], v[196:199], v[58:61]
	v_mfma_f32_16x16x32_bf16 v[46:49], v[164:167], v[204:207], v[46:49]
	v_mfma_f32_16x16x32_bf16 v[42:45], v[172:175], v[204:207], v[42:45]
	v_mfma_f32_16x16x32_bf16 v[30:33], v[164:167], v[212:215], v[30:33]
	v_mfma_f32_16x16x32_bf16 v[26:29], v[172:175], v[212:215], v[26:29]
	v_mfma_f32_16x16x32_bf16 v[14:17], v[164:167], v[220:223], v[14:17]
	v_mfma_f32_16x16x32_bf16 v[10:13], v[172:175], v[220:223], v[10:13]
	v_mfma_f32_16x16x32_bf16 v[54:57], v[176:179], v[192:195], v[54:57]
	v_mfma_f32_16x16x32_bf16 v[50:53], v[184:187], v[192:195], v[50:53]
	v_mfma_f32_16x16x32_bf16 v[38:41], v[176:179], v[200:203], v[38:41]
	v_mfma_f32_16x16x32_bf16 v[34:37], v[184:187], v[200:203], v[34:37]
	v_mfma_f32_16x16x32_bf16 v[22:25], v[176:179], v[208:211], v[22:25]
	v_mfma_f32_16x16x32_bf16 v[18:21], v[184:187], v[208:211], v[18:21]
	v_mfma_f32_16x16x32_bf16 v[6:9], v[176:179], v[216:219], v[6:9]
	v_mfma_f32_16x16x32_bf16 v[2:5], v[184:187], v[216:219], v[2:5]
	v_mfma_f32_16x16x32_bf16 v[54:57], v[180:183], v[196:199], v[54:57]
	v_mfma_f32_16x16x32_bf16 v[50:53], v[188:191], v[196:199], v[50:53]
	v_mfma_f32_16x16x32_bf16 v[38:41], v[180:183], v[204:207], v[38:41]
	v_mfma_f32_16x16x32_bf16 v[34:37], v[188:191], v[204:207], v[34:37]
	v_mfma_f32_16x16x32_bf16 v[22:25], v[180:183], v[212:215], v[22:25]
	v_mfma_f32_16x16x32_bf16 v[18:21], v[188:191], v[212:215], v[18:21]
	v_mfma_f32_16x16x32_bf16 v[6:9], v[180:183], v[220:223], v[6:9]
	v_mfma_f32_16x16x32_bf16 v[2:5], v[188:191], v[220:223], v[2:5]
	s_barrier
	s_add_i32 s67, 0, 0x18000
	v_add_u32_e32 v159, s67, v143
	s_add_i32 s70, 0, 0x1c000
	ds_read_b128 v[160:163], v159
	ds_read_b128 v[164:167], v159 offset:1024
	ds_read_b128 v[168:171], v159 offset:2048
	ds_read_b128 v[172:175], v159 offset:3072
	v_add_u32_e32 v159, s70, v143
	ds_read_b128 v[176:179], v159
	ds_read_b128 v[180:183], v159 offset:1024
	ds_read_b128 v[184:187], v159 offset:2048
	ds_read_b128 v[188:191], v159 offset:3072
	s_add_u32 s20, s20, s80
	s_addc_u32 s21, s21, 0
	s_mov_b32 m0, s30
	ds_read_b128 v[192:195], v146 offset:32768
	ds_read_b128 v[196:199], v146 offset:33792
	ds_read_b128 v[200:203], v146 offset:34816
	ds_read_b128 v[204:207], v146 offset:35840
	ds_read_b128 v[208:211], v146 offset:36864
	ds_read_b128 v[212:215], v146 offset:37888
	ds_read_b128 v[216:219], v146 offset:38912
	ds_read_b128 v[220:223], v146 offset:39936
	global_load_lds_dwordx4 v130, s[20:21]
	s_mov_b32 m0, s31
	s_nop 0
	global_load_lds_dwordx4 v132, s[20:21]
	s_waitcnt vmcnt(8)
	s_waitcnt lgkmcnt(0)
	s_barrier
	s_waitcnt lgkmcnt(0)
	v_mfma_f32_16x16x32_bf16 v[126:129], v[160:163], v[192:195], v[126:129]
	v_mfma_f32_16x16x32_bf16 v[122:125], v[168:171], v[192:195], v[122:125]
	v_mfma_f32_16x16x32_bf16 v[110:113], v[160:163], v[200:203], v[110:113]
	v_mfma_f32_16x16x32_bf16 v[106:109], v[168:171], v[200:203], v[106:109]
	v_mfma_f32_16x16x32_bf16 v[94:97], v[160:163], v[208:211], v[94:97]
	v_mfma_f32_16x16x32_bf16 v[90:93], v[168:171], v[208:211], v[90:93]
	v_mfma_f32_16x16x32_bf16 v[78:81], v[160:163], v[216:219], v[78:81]
	v_mfma_f32_16x16x32_bf16 v[74:77], v[168:171], v[216:219], v[74:77]
	v_mfma_f32_16x16x32_bf16 v[126:129], v[164:167], v[196:199], v[126:129]
	v_mfma_f32_16x16x32_bf16 v[122:125], v[172:175], v[196:199], v[122:125]
	v_mfma_f32_16x16x32_bf16 v[110:113], v[164:167], v[204:207], v[110:113]
	v_mfma_f32_16x16x32_bf16 v[106:109], v[172:175], v[204:207], v[106:109]
	v_mfma_f32_16x16x32_bf16 v[94:97], v[164:167], v[212:215], v[94:97]
	v_mfma_f32_16x16x32_bf16 v[90:93], v[172:175], v[212:215], v[90:93]
	v_mfma_f32_16x16x32_bf16 v[78:81], v[164:167], v[220:223], v[78:81]
	v_mfma_f32_16x16x32_bf16 v[74:77], v[172:175], v[220:223], v[74:77]
	v_mfma_f32_16x16x32_bf16 v[118:121], v[176:179], v[192:195], v[118:121]
	v_mfma_f32_16x16x32_bf16 v[114:117], v[184:187], v[192:195], v[114:117]
	v_mfma_f32_16x16x32_bf16 v[102:105], v[176:179], v[200:203], v[102:105]
	v_mfma_f32_16x16x32_bf16 v[98:101], v[184:187], v[200:203], v[98:101]
	v_mfma_f32_16x16x32_bf16 v[86:89], v[176:179], v[208:211], v[86:89]
	v_mfma_f32_16x16x32_bf16 v[82:85], v[184:187], v[208:211], v[82:85]
	v_mfma_f32_16x16x32_bf16 v[70:73], v[176:179], v[216:219], v[70:73]
	v_mfma_f32_16x16x32_bf16 v[66:69], v[184:187], v[216:219], v[66:69]
	v_mfma_f32_16x16x32_bf16 v[118:121], v[180:183], v[196:199], v[118:121]
	v_mfma_f32_16x16x32_bf16 v[114:117], v[188:191], v[196:199], v[114:117]
	v_mfma_f32_16x16x32_bf16 v[102:105], v[180:183], v[204:207], v[102:105]
	v_mfma_f32_16x16x32_bf16 v[98:101], v[188:191], v[204:207], v[98:101]
	v_mfma_f32_16x16x32_bf16 v[86:89], v[180:183], v[212:215], v[86:89]
	v_mfma_f32_16x16x32_bf16 v[82:85], v[188:191], v[212:215], v[82:85]
	v_mfma_f32_16x16x32_bf16 v[70:73], v[180:183], v[220:223], v[70:73]
	v_mfma_f32_16x16x32_bf16 v[66:69], v[188:191], v[220:223], v[66:69]
	s_barrier
	s_add_i32 s20, s67, s35
	s_mov_b32 m0, s20
	ds_read_b128 v[192:195], v146 offset:49152
	ds_read_b128 v[196:199], v146 offset:50176
	ds_read_b128 v[200:203], v146 offset:51200
	ds_read_b128 v[204:207], v146 offset:52224
	ds_read_b128 v[208:211], v146 offset:53248
	ds_read_b128 v[212:215], v146 offset:54272
	ds_read_b128 v[216:219], v146 offset:55296
	ds_read_b128 v[220:223], v146 offset:56320
	global_load_lds_dwordx4 v0, s[100:101]
	s_add_i32 m0, s20, 0x2000
	s_add_i32 s20, s70, s35
	global_load_lds_dwordx4 v134, s[100:101]
	s_add_u32 s100, s100, s80
	s_addc_u32 s101, s101, 0
	s_mov_b32 m0, s20
	s_nop 0
	global_load_lds_dwordx4 v0, s[100:101]
	s_add_i32 m0, s20, 0x2000
	s_nop 0
	global_load_lds_dwordx4 v134, s[100:101]
	s_mov_b32 m0, s56
	s_nop 0
	global_load_lds_dwordx4 v130, vcc
	s_mov_b32 m0, s57
	s_nop 0
	global_load_lds_dwordx4 v132, vcc
	s_waitcnt vmcnt(8)
	s_waitcnt lgkmcnt(0)
	s_barrier
	s_waitcnt lgkmcnt(0)
	v_mfma_f32_16x16x32_bf16 v[62:65], v[160:163], v[192:195], v[62:65]
	v_mfma_f32_16x16x32_bf16 v[58:61], v[168:171], v[192:195], v[58:61]
	v_mfma_f32_16x16x32_bf16 v[46:49], v[160:163], v[200:203], v[46:49]
	v_mfma_f32_16x16x32_bf16 v[42:45], v[168:171], v[200:203], v[42:45]
	v_mfma_f32_16x16x32_bf16 v[30:33], v[160:163], v[208:211], v[30:33]
	v_mfma_f32_16x16x32_bf16 v[26:29], v[168:171], v[208:211], v[26:29]
	v_mfma_f32_16x16x32_bf16 v[14:17], v[160:163], v[216:219], v[14:17]
	v_mfma_f32_16x16x32_bf16 v[10:13], v[168:171], v[216:219], v[10:13]
	v_mfma_f32_16x16x32_bf16 v[62:65], v[164:167], v[196:199], v[62:65]
	v_mfma_f32_16x16x32_bf16 v[58:61], v[172:175], v[196:199], v[58:61]
	v_mfma_f32_16x16x32_bf16 v[46:49], v[164:167], v[204:207], v[46:49]
	v_mfma_f32_16x16x32_bf16 v[42:45], v[172:175], v[204:207], v[42:45]
	v_mfma_f32_16x16x32_bf16 v[30:33], v[164:167], v[212:215], v[30:33]
	v_mfma_f32_16x16x32_bf16 v[26:29], v[172:175], v[212:215], v[26:29]
	v_mfma_f32_16x16x32_bf16 v[14:17], v[164:167], v[220:223], v[14:17]
	v_mfma_f32_16x16x32_bf16 v[10:13], v[172:175], v[220:223], v[10:13]
	v_mfma_f32_16x16x32_bf16 v[54:57], v[176:179], v[192:195], v[54:57]
	v_mfma_f32_16x16x32_bf16 v[50:53], v[184:187], v[192:195], v[50:53]
	v_mfma_f32_16x16x32_bf16 v[38:41], v[176:179], v[200:203], v[38:41]
	v_mfma_f32_16x16x32_bf16 v[34:37], v[184:187], v[200:203], v[34:37]
	v_mfma_f32_16x16x32_bf16 v[22:25], v[176:179], v[208:211], v[22:25]
	v_mfma_f32_16x16x32_bf16 v[18:21], v[184:187], v[208:211], v[18:21]
	v_mfma_f32_16x16x32_bf16 v[6:9], v[176:179], v[216:219], v[6:9]
	v_mfma_f32_16x16x32_bf16 v[2:5], v[184:187], v[216:219], v[2:5]
	v_mfma_f32_16x16x32_bf16 v[54:57], v[180:183], v[196:199], v[54:57]
	v_mfma_f32_16x16x32_bf16 v[50:53], v[188:191], v[196:199], v[50:53]
	v_mfma_f32_16x16x32_bf16 v[38:41], v[180:183], v[204:207], v[38:41]
	v_mfma_f32_16x16x32_bf16 v[34:37], v[188:191], v[204:207], v[34:37]
	v_mfma_f32_16x16x32_bf16 v[22:25], v[180:183], v[212:215], v[22:25]
	v_mfma_f32_16x16x32_bf16 v[18:21], v[188:191], v[212:215], v[18:21]
	v_mfma_f32_16x16x32_bf16 v[6:9], v[180:183], v[220:223], v[6:9]
	v_mfma_f32_16x16x32_bf16 v[2:5], v[188:191], v[220:223], v[2:5]
	s_barrier
	s_add_u32 s16, s16, 0x100
	s_addc_u32 s17, s17, 0
	s_add_u32 s64, s64, 0x100
	s_addc_u32 s65, s65, 0
	s_cmp_ge_u32 s66, s55
	s_mov_b32 s20, s66
	s_cbranch_scc0 .LBB0_334
	s_and_b64 vcc, exec, s[10:11]
	s_cbranch_vccz .LBB0_337
	s_barrier

.LBB0_360:
	s_add_i32 s30, s10, 2
	s_add_u32 s31, s2, 0x80
	s_addc_u32 s11, s3, 0
	s_add_i32 s35, 0, 0x10000
	s_cmp_eq_u32 s58, s10
	s_cselect_b32 s11, s1, s11
	s_cselect_b32 s10, s0, s31
	v_add_u32_e32 v148, s35, v160
	s_cselect_b32 s67, s7, s29
	s_cselect_b32 s66, s6, s19
	s_add_i32 s31, 0, 0x14000
	ds_read_b128 v[140:143], v148
	ds_read_b128 v[144:147], v148 offset:1024
	ds_read_b128 v[180:183], v148 offset:2048
	ds_read_b128 v[184:187], v148 offset:3072
	v_add_u32_e32 v148, s31, v160
	ds_read_b128 v[188:191], v148
	ds_read_b128 v[192:195], v148 offset:1024
	ds_read_b128 v[196:199], v148 offset:2048
	ds_read_b128 v[200:203], v148 offset:3072
	s_add_i32 m0, s23, 0xc000
	ds_read_b128 v[204:207], v172
	ds_read_b128 v[208:211], v172 offset:1024
	ds_read_b128 v[212:215], v172 offset:2048
	ds_read_b128 v[216:219], v172 offset:3072
	ds_read_b128 v[220:223], v172 offset:4096
	ds_read_b128 v[224:227], v172 offset:5120
	ds_read_b128 v[228:231], v172 offset:6144
	ds_read_b128 v[232:235], v172 offset:7168
	global_load_lds_dwordx4 v136, s[2:3]
	s_add_i32 m0, s23, 0xe000
	s_nop 0
	global_load_lds_dwordx4 v138, s[2:3]
	s_waitcnt vmcnt(8)
	s_waitcnt lgkmcnt(0)
	s_barrier
	s_waitcnt lgkmcnt(0)
	v_mfma_f32_16x16x32_bf16 v[126:129], v[140:143], v[204:207], v[126:129]
	v_mfma_f32_16x16x32_bf16 v[122:125], v[180:183], v[204:207], v[122:125]
	v_mfma_f32_16x16x32_bf16 v[110:113], v[140:143], v[212:215], v[110:113]
	v_mfma_f32_16x16x32_bf16 v[106:109], v[180:183], v[212:215], v[106:109]
	v_mfma_f32_16x16x32_bf16 v[94:97], v[140:143], v[220:223], v[94:97]
	v_mfma_f32_16x16x32_bf16 v[90:93], v[180:183], v[220:223], v[90:93]
	v_mfma_f32_16x16x32_bf16 v[78:81], v[140:143], v[228:231], v[78:81]
	v_mfma_f32_16x16x32_bf16 v[74:77], v[180:183], v[228:231], v[74:77]
	v_mfma_f32_16x16x32_bf16 v[126:129], v[144:147], v[208:211], v[126:129]
	v_mfma_f32_16x16x32_bf16 v[122:125], v[184:187], v[208:211], v[122:125]
	v_mfma_f32_16x16x32_bf16 v[110:113], v[144:147], v[216:219], v[110:113]
	v_mfma_f32_16x16x32_bf16 v[106:109], v[184:187], v[216:219], v[106:109]
	v_mfma_f32_16x16x32_bf16 v[94:97], v[144:147], v[224:227], v[94:97]
	v_mfma_f32_16x16x32_bf16 v[90:93], v[184:187], v[224:227], v[90:93]
	v_mfma_f32_16x16x32_bf16 v[78:81], v[144:147], v[232:235], v[78:81]
	v_mfma_f32_16x16x32_bf16 v[74:77], v[184:187], v[232:235], v[74:77]
	v_mfma_f32_16x16x32_bf16 v[118:121], v[188:191], v[204:207], v[118:121]
	v_mfma_f32_16x16x32_bf16 v[114:117], v[196:199], v[204:207], v[114:117]
	v_mfma_f32_16x16x32_bf16 v[102:105], v[188:191], v[212:215], v[102:105]
	v_mfma_f32_16x16x32_bf16 v[98:101], v[196:199], v[212:215], v[98:101]
	v_mfma_f32_16x16x32_bf16 v[86:89], v[188:191], v[220:223], v[86:89]
	v_mfma_f32_16x16x32_bf16 v[82:85], v[196:199], v[220:223], v[82:85]
	v_mfma_f32_16x16x32_bf16 v[70:73], v[188:191], v[228:231], v[70:73]
	v_mfma_f32_16x16x32_bf16 v[66:69], v[196:199], v[228:231], v[66:69]
	v_mfma_f32_16x16x32_bf16 v[118:121], v[192:195], v[208:211], v[118:121]
	v_mfma_f32_16x16x32_bf16 v[114:117], v[200:203], v[208:211], v[114:117]
	v_mfma_f32_16x16x32_bf16 v[102:105], v[192:195], v[216:219], v[102:105]
	v_mfma_f32_16x16x32_bf16 v[98:101], v[200:203], v[216:219], v[98:101]
	v_mfma_f32_16x16x32_bf16 v[86:89], v[192:195], v[224:227], v[86:89]
	v_mfma_f32_16x16x32_bf16 v[82:85], v[200:203], v[224:227], v[82:85]
	v_mfma_f32_16x16x32_bf16 v[70:73], v[192:195], v[232:235], v[70:73]
	v_mfma_f32_16x16x32_bf16 v[66:69], v[200:203], v[232:235], v[66:69]
	s_barrier
	s_add_i32 s35, s35, s20
	s_mov_b32 m0, s35
	ds_read_b128 v[204:207], v172 offset:16384
	ds_read_b128 v[208:211], v172 offset:17408
	ds_read_b128 v[212:215], v172 offset:18432
	ds_read_b128 v[216:219], v172 offset:19456
	ds_read_b128 v[220:223], v172 offset:20480
	ds_read_b128 v[224:227], v172 offset:21504
	ds_read_b128 v[228:231], v172 offset:22528
	ds_read_b128 v[232:235], v172 offset:23552
	global_load_lds_dwordx4 v0, s[66:67]
	s_add_i32 m0, s35, 0x2000
	s_nop 0
	global_load_lds_dwordx4 v134, s[66:67]
	s_add_u32 s66, s66, s16
	s_addc_u32 s67, s67, 0
	s_add_i32 s31, s31, s20
	s_mov_b32 m0, s31
	s_nop 0
	global_load_lds_dwordx4 v0, s[66:67]
	s_add_i32 m0, s31, 0x2000
	s_nop 0
	global_load_lds_dwordx4 v134, s[66:67]
	s_mov_b32 m0, s23
	s_nop 0
	global_load_lds_dwordx4 v130, s[10:11]
	s_mov_b32 m0, s52
	s_nop 0
	global_load_lds_dwordx4 v132, s[10:11]
	s_sub_u32 s100, s66, s16
	s_subb_u32 s101, s67, 0
	s_add_u32 s100, s100, s94
	s_addc_u32 s101, s101, s95
	s_add_u32 vcc_lo, s10, s94
	s_addc_u32 vcc_hi, s11, s95
	s_waitcnt vmcnt(8)
	s_waitcnt lgkmcnt(0)
	s_barrier
	s_waitcnt lgkmcnt(0)
	v_mfma_f32_16x16x32_bf16 v[62:65], v[140:143], v[204:207], v[62:65]
	v_mfma_f32_16x16x32_bf16 v[58:61], v[180:183], v[204:207], v[58:61]
	v_mfma_f32_16x16x32_bf16 v[46:49], v[140:143], v[212:215], v[46:49]
	v_mfma_f32_16x16x32_bf16 v[42:45], v[180:183], v[212:215], v[42:45]
	v_mfma_f32_16x16x32_bf16 v[30:33], v[140:143], v[220:223], v[30:33]
	v_mfma_f32_16x16x32_bf16 v[26:29], v[180:183], v[220:223], v[26:29]
	v_mfma_f32_16x16x32_bf16 v[14:17], v[140:143], v[228:231], v[14:17]
	v_mfma_f32_16x16x32_bf16 v[10:13], v[180:183], v[228:231], v[10:13]
	v_mfma_f32_16x16x32_bf16 v[62:65], v[144:147], v[208:211], v[62:65]
	v_mfma_f32_16x16x32_bf16 v[58:61], v[184:187], v[208:211], v[58:61]
	v_mfma_f32_16x16x32_bf16 v[46:49], v[144:147], v[216:219], v[46:49]
	v_mfma_f32_16x16x32_bf16 v[42:45], v[184:187], v[216:219], v[42:45]
	v_mfma_f32_16x16x32_bf16 v[30:33], v[144:147], v[224:227], v[30:33]
	v_mfma_f32_16x16x32_bf16 v[26:29], v[184:187], v[224:227], v[26:29]
	v_mfma_f32_16x16x32_bf16 v[14:17], v[144:147], v[232:235], v[14:17]
	v_mfma_f32_16x16x32_bf16 v[10:13], v[184:187], v[232:235], v[10:13]
	v_mfma_f32_16x16x32_bf16 v[54:57], v[188:191], v[204:207], v[54:57]
	v_mfma_f32_16x16x32_bf16 v[50:53], v[196:199], v[204:207], v[50:53]
	v_mfma_f32_16x16x32_bf16 v[38:41], v[188:191], v[212:215], v[38:41]
	v_mfma_f32_16x16x32_bf16 v[34:37], v[196:199], v[212:215], v[34:37]
	v_mfma_f32_16x16x32_bf16 v[22:25], v[188:191], v[220:223], v[22:25]
	v_mfma_f32_16x16x32_bf16 v[18:21], v[196:199], v[220:223], v[18:21]
	v_mfma_f32_16x16x32_bf16 v[6:9], v[188:191], v[228:231], v[6:9]
	v_mfma_f32_16x16x32_bf16 v[2:5], v[196:199], v[228:231], v[2:5]
	v_mfma_f32_16x16x32_bf16 v[54:57], v[192:195], v[208:211], v[54:57]
	v_mfma_f32_16x16x32_bf16 v[50:53], v[200:203], v[208:211], v[50:53]
	v_mfma_f32_16x16x32_bf16 v[38:41], v[192:195], v[216:219], v[38:41]
	v_mfma_f32_16x16x32_bf16 v[34:37], v[200:203], v[216:219], v[34:37]
	v_mfma_f32_16x16x32_bf16 v[22:25], v[192:195], v[224:227], v[22:25]
	v_mfma_f32_16x16x32_bf16 v[18:21], v[200:203], v[224:227], v[18:21]
	v_mfma_f32_16x16x32_bf16 v[6:9], v[192:195], v[232:235], v[6:9]
	v_mfma_f32_16x16x32_bf16 v[2:5], v[200:203], v[232:235], v[2:5]
	s_barrier
	s_add_i32 s31, 0, 0x18000
	s_add_i32 s35, 0, 0x1c000
	v_add_u32_e32 v184, s31, v160
	v_add_u32_e32 v200, s35, v160
	ds_read_b128 v[140:143], v184
	ds_read_b128 v[144:147], v184 offset:1024
	ds_read_b128 v[180:183], v184 offset:2048
	ds_read_b128 v[184:187], v184 offset:3072
	ds_read_b128 v[188:191], v200
	ds_read_b128 v[192:195], v200 offset:1024
	ds_read_b128 v[196:199], v200 offset:2048
	ds_read_b128 v[200:203], v200 offset:3072
	s_add_u32 s10, s10, s16
	s_addc_u32 s11, s11, 0
	s_mov_b32 m0, s53
	ds_read_b128 v[204:207], v172 offset:32768
	ds_read_b128 v[208:211], v172 offset:33792
	ds_read_b128 v[212:215], v172 offset:34816
	ds_read_b128 v[216:219], v172 offset:35840
	ds_read_b128 v[220:223], v172 offset:36864
	ds_read_b128 v[224:227], v172 offset:37888
	ds_read_b128 v[228:231], v172 offset:38912
	ds_read_b128 v[232:235], v172 offset:39936
	global_load_lds_dwordx4 v130, s[10:11]
	s_mov_b32 m0, s54
	s_nop 0
	global_load_lds_dwordx4 v132, s[10:11]
	s_waitcnt vmcnt(8)
	s_waitcnt lgkmcnt(0)
	s_barrier
	s_waitcnt lgkmcnt(0)
	v_mfma_f32_16x16x32_bf16 v[126:129], v[140:143], v[204:207], v[126:129]
	v_mfma_f32_16x16x32_bf16 v[122:125], v[180:183], v[204:207], v[122:125]
	v_mfma_f32_16x16x32_bf16 v[110:113], v[140:143], v[212:215], v[110:113]
	v_mfma_f32_16x16x32_bf16 v[106:109], v[180:183], v[212:215], v[106:109]
	v_mfma_f32_16x16x32_bf16 v[94:97], v[140:143], v[220:223], v[94:97]
	v_mfma_f32_16x16x32_bf16 v[90:93], v[180:183], v[220:223], v[90:93]
	v_mfma_f32_16x16x32_bf16 v[78:81], v[140:143], v[228:231], v[78:81]
	v_mfma_f32_16x16x32_bf16 v[74:77], v[180:183], v[228:231], v[74:77]
	v_mfma_f32_16x16x32_bf16 v[126:129], v[144:147], v[208:211], v[126:129]
	v_mfma_f32_16x16x32_bf16 v[122:125], v[184:187], v[208:211], v[122:125]
	v_mfma_f32_16x16x32_bf16 v[110:113], v[144:147], v[216:219], v[110:113]
	v_mfma_f32_16x16x32_bf16 v[106:109], v[184:187], v[216:219], v[106:109]
	v_mfma_f32_16x16x32_bf16 v[94:97], v[144:147], v[224:227], v[94:97]
	v_mfma_f32_16x16x32_bf16 v[90:93], v[184:187], v[224:227], v[90:93]
	v_mfma_f32_16x16x32_bf16 v[78:81], v[144:147], v[232:235], v[78:81]
	v_mfma_f32_16x16x32_bf16 v[74:77], v[184:187], v[232:235], v[74:77]
	v_mfma_f32_16x16x32_bf16 v[118:121], v[188:191], v[204:207], v[118:121]
	v_mfma_f32_16x16x32_bf16 v[114:117], v[196:199], v[204:207], v[114:117]
	v_mfma_f32_16x16x32_bf16 v[102:105], v[188:191], v[212:215], v[102:105]
	v_mfma_f32_16x16x32_bf16 v[98:101], v[196:199], v[212:215], v[98:101]
	v_mfma_f32_16x16x32_bf16 v[86:89], v[188:191], v[220:223], v[86:89]
	v_mfma_f32_16x16x32_bf16 v[82:85], v[196:199], v[220:223], v[82:85]
	v_mfma_f32_16x16x32_bf16 v[70:73], v[188:191], v[228:231], v[70:73]
	v_mfma_f32_16x16x32_bf16 v[66:69], v[196:199], v[228:231], v[66:69]
	v_mfma_f32_16x16x32_bf16 v[118:121], v[192:195], v[208:211], v[118:121]
	v_mfma_f32_16x16x32_bf16 v[114:117], v[200:203], v[208:211], v[114:117]
	v_mfma_f32_16x16x32_bf16 v[102:105], v[192:195], v[216:219], v[102:105]
	v_mfma_f32_16x16x32_bf16 v[98:101], v[200:203], v[216:219], v[98:101]
	v_mfma_f32_16x16x32_bf16 v[86:89], v[192:195], v[224:227], v[86:89]
	v_mfma_f32_16x16x32_bf16 v[82:85], v[200:203], v[224:227], v[82:85]
	v_mfma_f32_16x16x32_bf16 v[70:73], v[192:195], v[232:235], v[70:73]
	v_mfma_f32_16x16x32_bf16 v[66:69], v[200:203], v[232:235], v[66:69]
	s_barrier
	s_add_i32 s10, s31, s20
	s_mov_b32 m0, s10
	ds_read_b128 v[204:207], v172 offset:49152
	ds_read_b128 v[208:211], v172 offset:50176
	ds_read_b128 v[212:215], v172 offset:51200
	ds_read_b128 v[216:219], v172 offset:52224
	ds_read_b128 v[220:223], v172 offset:53248
	ds_read_b128 v[224:227], v172 offset:54272
	ds_read_b128 v[228:231], v172 offset:55296
	ds_read_b128 v[232:235], v172 offset:56320
	global_load_lds_dwordx4 v0, s[100:101]
	s_add_i32 m0, s10, 0x2000
	s_add_i32 s10, s35, s20
	global_load_lds_dwordx4 v134, s[100:101]
	s_add_u32 s100, s100, s16
	s_addc_u32 s101, s101, 0
	s_mov_b32 m0, s10
	s_nop 0
	global_load_lds_dwordx4 v0, s[100:101]
	s_add_i32 m0, s10, 0x2000
	s_nop 0
	global_load_lds_dwordx4 v134, s[100:101]
	s_mov_b32 m0, s56
	s_nop 0
	global_load_lds_dwordx4 v130, vcc
	s_mov_b32 m0, s57
	s_nop 0
	global_load_lds_dwordx4 v132, vcc
	s_waitcnt vmcnt(8)
	s_waitcnt lgkmcnt(0)
	s_barrier
	s_waitcnt lgkmcnt(0)
	v_mfma_f32_16x16x32_bf16 v[62:65], v[140:143], v[204:207], v[62:65]
	v_mfma_f32_16x16x32_bf16 v[58:61], v[180:183], v[204:207], v[58:61]
	v_mfma_f32_16x16x32_bf16 v[46:49], v[140:143], v[212:215], v[46:49]
	v_mfma_f32_16x16x32_bf16 v[42:45], v[180:183], v[212:215], v[42:45]
	v_mfma_f32_16x16x32_bf16 v[30:33], v[140:143], v[220:223], v[30:33]
	v_mfma_f32_16x16x32_bf16 v[26:29], v[180:183], v[220:223], v[26:29]
	v_mfma_f32_16x16x32_bf16 v[14:17], v[140:143], v[228:231], v[14:17]
	v_mfma_f32_16x16x32_bf16 v[10:13], v[180:183], v[228:231], v[10:13]
	v_mfma_f32_16x16x32_bf16 v[62:65], v[144:147], v[208:211], v[62:65]
	v_mfma_f32_16x16x32_bf16 v[58:61], v[184:187], v[208:211], v[58:61]
	v_mfma_f32_16x16x32_bf16 v[46:49], v[144:147], v[216:219], v[46:49]
	v_mfma_f32_16x16x32_bf16 v[42:45], v[184:187], v[216:219], v[42:45]
	v_mfma_f32_16x16x32_bf16 v[30:33], v[144:147], v[224:227], v[30:33]
	v_mfma_f32_16x16x32_bf16 v[26:29], v[184:187], v[224:227], v[26:29]
	v_mfma_f32_16x16x32_bf16 v[14:17], v[144:147], v[232:235], v[14:17]
	v_mfma_f32_16x16x32_bf16 v[10:13], v[184:187], v[232:235], v[10:13]
	v_mfma_f32_16x16x32_bf16 v[54:57], v[188:191], v[204:207], v[54:57]
	v_mfma_f32_16x16x32_bf16 v[50:53], v[196:199], v[204:207], v[50:53]
	v_mfma_f32_16x16x32_bf16 v[38:41], v[188:191], v[212:215], v[38:41]
	v_mfma_f32_16x16x32_bf16 v[34:37], v[196:199], v[212:215], v[34:37]
	v_mfma_f32_16x16x32_bf16 v[22:25], v[188:191], v[220:223], v[22:25]
	v_mfma_f32_16x16x32_bf16 v[18:21], v[196:199], v[220:223], v[18:21]
	v_mfma_f32_16x16x32_bf16 v[6:9], v[188:191], v[228:231], v[6:9]
	v_mfma_f32_16x16x32_bf16 v[2:5], v[196:199], v[228:231], v[2:5]
	v_mfma_f32_16x16x32_bf16 v[54:57], v[192:195], v[208:211], v[54:57]
	v_mfma_f32_16x16x32_bf16 v[50:53], v[200:203], v[208:211], v[50:53]
	v_mfma_f32_16x16x32_bf16 v[38:41], v[192:195], v[216:219], v[38:41]
	v_mfma_f32_16x16x32_bf16 v[34:37], v[200:203], v[216:219], v[34:37]
	v_mfma_f32_16x16x32_bf16 v[22:25], v[192:195], v[224:227], v[22:25]
	v_mfma_f32_16x16x32_bf16 v[18:21], v[200:203], v[224:227], v[18:21]
	v_mfma_f32_16x16x32_bf16 v[6:9], v[192:195], v[232:235], v[6:9]
	v_mfma_f32_16x16x32_bf16 v[2:5], v[200:203], v[232:235], v[2:5]
	s_barrier
	s_add_u32 s2, s2, 0x100
	s_addc_u32 s3, s3, 0
	s_add_u32 s19, s19, 0x100
	s_addc_u32 s29, s29, 0
	s_cmp_ge_u32 s30, s55
	s_mov_b32 s10, s30
	s_cbranch_scc0 .LBB0_360
	s_and_b64 vcc, exec, s[14:15]
	s_cbranch_vccz .LBB0_363
	s_barrier

.LBB0_419:
	s_add_i32 s66, s20, 2
	s_add_u32 s67, s16, 0x80
	s_addc_u32 s21, s17, 0
	s_add_i32 s72, 0, 0x10000
	s_cmp_eq_u32 s58, s20
	s_cselect_b32 s21, s1, s21
	s_cselect_b32 s20, s0, s67
	v_add_u32_e32 v140, s72, v143
	s_cselect_b32 s71, s15, s65
	s_cselect_b32 s70, s14, s64
	s_add_i32 s67, 0, 0x14000
	ds_read_b128 v[160:163], v140
	ds_read_b128 v[164:167], v140 offset:1024
	ds_read_b128 v[168:171], v140 offset:2048
	ds_read_b128 v[172:175], v140 offset:3072
	v_add_u32_e32 v140, s67, v143
	ds_read_b128 v[176:179], v140
	ds_read_b128 v[180:183], v140 offset:1024
	ds_read_b128 v[184:187], v140 offset:2048
	ds_read_b128 v[188:191], v140 offset:3072
	s_add_i32 m0, s35, 0xc000
	ds_read_b128 v[192:195], v146
	ds_read_b128 v[196:199], v146 offset:1024
	ds_read_b128 v[200:203], v146 offset:2048
	ds_read_b128 v[204:207], v146 offset:3072
	ds_read_b128 v[208:211], v146 offset:4096
	ds_read_b128 v[212:215], v146 offset:5120
	ds_read_b128 v[216:219], v146 offset:6144
	ds_read_b128 v[220:223], v146 offset:7168
	global_load_lds_dwordx4 v136, s[16:17]
	s_add_i32 m0, s35, 0xe000
	s_nop 0
	global_load_lds_dwordx4 v138, s[16:17]
	s_waitcnt vmcnt(8)
	s_waitcnt lgkmcnt(0)
	s_barrier
	s_waitcnt lgkmcnt(0)
	v_mfma_f32_16x16x32_bf16 v[126:129], v[160:163], v[192:195], v[126:129]
	v_mfma_f32_16x16x32_bf16 v[122:125], v[168:171], v[192:195], v[122:125]
	v_mfma_f32_16x16x32_bf16 v[110:113], v[160:163], v[200:203], v[110:113]
	v_mfma_f32_16x16x32_bf16 v[106:109], v[168:171], v[200:203], v[106:109]
	v_mfma_f32_16x16x32_bf16 v[94:97], v[160:163], v[208:211], v[94:97]
	v_mfma_f32_16x16x32_bf16 v[90:93], v[168:171], v[208:211], v[90:93]
	v_mfma_f32_16x16x32_bf16 v[78:81], v[160:163], v[216:219], v[78:81]
	v_mfma_f32_16x16x32_bf16 v[74:77], v[168:171], v[216:219], v[74:77]
	v_mfma_f32_16x16x32_bf16 v[126:129], v[164:167], v[196:199], v[126:129]
	v_mfma_f32_16x16x32_bf16 v[122:125], v[172:175], v[196:199], v[122:125]
	v_mfma_f32_16x16x32_bf16 v[110:113], v[164:167], v[204:207], v[110:113]
	v_mfma_f32_16x16x32_bf16 v[106:109], v[172:175], v[204:207], v[106:109]
	v_mfma_f32_16x16x32_bf16 v[94:97], v[164:167], v[212:215], v[94:97]
	v_mfma_f32_16x16x32_bf16 v[90:93], v[172:175], v[212:215], v[90:93]
	v_mfma_f32_16x16x32_bf16 v[78:81], v[164:167], v[220:223], v[78:81]
	v_mfma_f32_16x16x32_bf16 v[74:77], v[172:175], v[220:223], v[74:77]
	v_mfma_f32_16x16x32_bf16 v[118:121], v[176:179], v[192:195], v[118:121]
	v_mfma_f32_16x16x32_bf16 v[114:117], v[184:187], v[192:195], v[114:117]
	v_mfma_f32_16x16x32_bf16 v[102:105], v[176:179], v[200:203], v[102:105]
	v_mfma_f32_16x16x32_bf16 v[98:101], v[184:187], v[200:203], v[98:101]
	v_mfma_f32_16x16x32_bf16 v[86:89], v[176:179], v[208:211], v[86:89]
	v_mfma_f32_16x16x32_bf16 v[82:85], v[184:187], v[208:211], v[82:85]
	v_mfma_f32_16x16x32_bf16 v[70:73], v[176:179], v[216:219], v[70:73]
	v_mfma_f32_16x16x32_bf16 v[66:69], v[184:187], v[216:219], v[66:69]
	v_mfma_f32_16x16x32_bf16 v[118:121], v[180:183], v[196:199], v[118:121]
	v_mfma_f32_16x16x32_bf16 v[114:117], v[188:191], v[196:199], v[114:117]
	v_mfma_f32_16x16x32_bf16 v[102:105], v[180:183], v[204:207], v[102:105]
	v_mfma_f32_16x16x32_bf16 v[98:101], v[188:191], v[204:207], v[98:101]
	v_mfma_f32_16x16x32_bf16 v[86:89], v[180:183], v[212:215], v[86:89]
	v_mfma_f32_16x16x32_bf16 v[82:85], v[188:191], v[212:215], v[82:85]
	v_mfma_f32_16x16x32_bf16 v[70:73], v[180:183], v[220:223], v[70:73]
	v_mfma_f32_16x16x32_bf16 v[66:69], v[188:191], v[220:223], v[66:69]
	s_barrier
	s_add_i32 s72, s72, s30
	s_mov_b32 m0, s72
	ds_read_b128 v[192:195], v146 offset:16384
	ds_read_b128 v[196:199], v146 offset:17408
	ds_read_b128 v[200:203], v146 offset:18432
	ds_read_b128 v[204:207], v146 offset:19456
	ds_read_b128 v[208:211], v146 offset:20480
	ds_read_b128 v[212:215], v146 offset:21504
	ds_read_b128 v[216:219], v146 offset:22528
	ds_read_b128 v[220:223], v146 offset:23552
	global_load_lds_dwordx4 v0, s[70:71]
	s_add_i32 m0, s72, 0x2000
	s_nop 0
	global_load_lds_dwordx4 v134, s[70:71]
	s_add_u32 s70, s70, s80
	s_addc_u32 s71, s71, 0
	s_add_i32 s67, s67, s30
	s_mov_b32 m0, s67
	s_nop 0
	global_load_lds_dwordx4 v0, s[70:71]
	s_add_i32 m0, s67, 0x2000
	s_nop 0
	global_load_lds_dwordx4 v134, s[70:71]
	s_mov_b32 m0, s35
	s_nop 0
	global_load_lds_dwordx4 v130, s[20:21]
	s_mov_b32 m0, s52
	s_nop 0
	global_load_lds_dwordx4 v132, s[20:21]
	s_sub_u32 s100, s70, s80
	s_subb_u32 s101, s71, 0
	s_add_u32 s100, s100, s94
	s_addc_u32 s101, s101, s95
	s_add_u32 vcc_lo, s20, s94
	s_addc_u32 vcc_hi, s21, s95
	s_waitcnt vmcnt(8)
	s_waitcnt lgkmcnt(0)
	s_barrier
	s_waitcnt lgkmcnt(0)
	v_mfma_f32_16x16x32_bf16 v[62:65], v[160:163], v[192:195], v[62:65]
	v_mfma_f32_16x16x32_bf16 v[58:61], v[168:171], v[192:195], v[58:61]
	v_mfma_f32_16x16x32_bf16 v[46:49], v[160:163], v[200:203], v[46:49]
	v_mfma_f32_16x16x32_bf16 v[42:45], v[168:171], v[200:203], v[42:45]
	v_mfma_f32_16x16x32_bf16 v[30:33], v[160:163], v[208:211], v[30:33]
	v_mfma_f32_16x16x32_bf16 v[26:29], v[168:171], v[208:211], v[26:29]
	v_mfma_f32_16x16x32_bf16 v[14:17], v[160:163], v[216:219], v[14:17]
	v_mfma_f32_16x16x32_bf16 v[10:13], v[168:171], v[216:219], v[10:13]
	v_mfma_f32_16x16x32_bf16 v[62:65], v[164:167], v[196:199], v[62:65]
	v_mfma_f32_16x16x32_bf16 v[58:61], v[172:175], v[196:199], v[58:61]
	v_mfma_f32_16x16x32_bf16 v[46:49], v[164:167], v[204:207], v[46:49]
	v_mfma_f32_16x16x32_bf16 v[42:45], v[172:175], v[204:207], v[42:45]
	v_mfma_f32_16x16x32_bf16 v[30:33], v[164:167], v[212:215], v[30:33]
	v_mfma_f32_16x16x32_bf16 v[26:29], v[172:175], v[212:215], v[26:29]
	v_mfma_f32_16x16x32_bf16 v[14:17], v[164:167], v[220:223], v[14:17]
	v_mfma_f32_16x16x32_bf16 v[10:13], v[172:175], v[220:223], v[10:13]
	v_mfma_f32_16x16x32_bf16 v[54:57], v[176:179], v[192:195], v[54:57]
	v_mfma_f32_16x16x32_bf16 v[50:53], v[184:187], v[192:195], v[50:53]
	v_mfma_f32_16x16x32_bf16 v[38:41], v[176:179], v[200:203], v[38:41]
	v_mfma_f32_16x16x32_bf16 v[34:37], v[184:187], v[200:203], v[34:37]
	v_mfma_f32_16x16x32_bf16 v[22:25], v[176:179], v[208:211], v[22:25]
	v_mfma_f32_16x16x32_bf16 v[18:21], v[184:187], v[208:211], v[18:21]
	v_mfma_f32_16x16x32_bf16 v[6:9], v[176:179], v[216:219], v[6:9]
	v_mfma_f32_16x16x32_bf16 v[2:5], v[184:187], v[216:219], v[2:5]
	v_mfma_f32_16x16x32_bf16 v[54:57], v[180:183], v[196:199], v[54:57]
	v_mfma_f32_16x16x32_bf16 v[50:53], v[188:191], v[196:199], v[50:53]
	v_mfma_f32_16x16x32_bf16 v[38:41], v[180:183], v[204:207], v[38:41]
	v_mfma_f32_16x16x32_bf16 v[34:37], v[188:191], v[204:207], v[34:37]
	v_mfma_f32_16x16x32_bf16 v[22:25], v[180:183], v[212:215], v[22:25]
	v_mfma_f32_16x16x32_bf16 v[18:21], v[188:191], v[212:215], v[18:21]
	v_mfma_f32_16x16x32_bf16 v[6:9], v[180:183], v[220:223], v[6:9]
	v_mfma_f32_16x16x32_bf16 v[2:5], v[188:191], v[220:223], v[2:5]
	s_barrier
	s_add_i32 s67, 0, 0x18000
	v_add_u32_e32 v159, s67, v143
	s_add_i32 s70, 0, 0x1c000
	ds_read_b128 v[160:163], v159
	ds_read_b128 v[164:167], v159 offset:1024
	ds_read_b128 v[168:171], v159 offset:2048
	ds_read_b128 v[172:175], v159 offset:3072
	v_add_u32_e32 v159, s70, v143
	ds_read_b128 v[176:179], v159
	ds_read_b128 v[180:183], v159 offset:1024
	ds_read_b128 v[184:187], v159 offset:2048
	ds_read_b128 v[188:191], v159 offset:3072
	s_add_u32 s20, s20, s80
	s_addc_u32 s21, s21, 0
	s_mov_b32 m0, s53
	ds_read_b128 v[192:195], v146 offset:32768
	ds_read_b128 v[196:199], v146 offset:33792
	ds_read_b128 v[200:203], v146 offset:34816
	ds_read_b128 v[204:207], v146 offset:35840
	ds_read_b128 v[208:211], v146 offset:36864
	ds_read_b128 v[212:215], v146 offset:37888
	ds_read_b128 v[216:219], v146 offset:38912
	ds_read_b128 v[220:223], v146 offset:39936
	global_load_lds_dwordx4 v130, s[20:21]
	s_mov_b32 m0, s54
	s_nop 0
	global_load_lds_dwordx4 v132, s[20:21]
	s_waitcnt vmcnt(8)
	s_waitcnt lgkmcnt(0)
	s_barrier
	s_waitcnt lgkmcnt(0)
	v_mfma_f32_16x16x32_bf16 v[126:129], v[160:163], v[192:195], v[126:129]
	v_mfma_f32_16x16x32_bf16 v[122:125], v[168:171], v[192:195], v[122:125]
	v_mfma_f32_16x16x32_bf16 v[110:113], v[160:163], v[200:203], v[110:113]
	v_mfma_f32_16x16x32_bf16 v[106:109], v[168:171], v[200:203], v[106:109]
	v_mfma_f32_16x16x32_bf16 v[94:97], v[160:163], v[208:211], v[94:97]
	v_mfma_f32_16x16x32_bf16 v[90:93], v[168:171], v[208:211], v[90:93]
	v_mfma_f32_16x16x32_bf16 v[78:81], v[160:163], v[216:219], v[78:81]
	v_mfma_f32_16x16x32_bf16 v[74:77], v[168:171], v[216:219], v[74:77]
	v_mfma_f32_16x16x32_bf16 v[126:129], v[164:167], v[196:199], v[126:129]
	v_mfma_f32_16x16x32_bf16 v[122:125], v[172:175], v[196:199], v[122:125]
	v_mfma_f32_16x16x32_bf16 v[110:113], v[164:167], v[204:207], v[110:113]
	v_mfma_f32_16x16x32_bf16 v[106:109], v[172:175], v[204:207], v[106:109]
	v_mfma_f32_16x16x32_bf16 v[94:97], v[164:167], v[212:215], v[94:97]
	v_mfma_f32_16x16x32_bf16 v[90:93], v[172:175], v[212:215], v[90:93]
	v_mfma_f32_16x16x32_bf16 v[78:81], v[164:167], v[220:223], v[78:81]
	v_mfma_f32_16x16x32_bf16 v[74:77], v[172:175], v[220:223], v[74:77]
	v_mfma_f32_16x16x32_bf16 v[118:121], v[176:179], v[192:195], v[118:121]
	v_mfma_f32_16x16x32_bf16 v[114:117], v[184:187], v[192:195], v[114:117]
	v_mfma_f32_16x16x32_bf16 v[102:105], v[176:179], v[200:203], v[102:105]
	v_mfma_f32_16x16x32_bf16 v[98:101], v[184:187], v[200:203], v[98:101]
	v_mfma_f32_16x16x32_bf16 v[86:89], v[176:179], v[208:211], v[86:89]
	v_mfma_f32_16x16x32_bf16 v[82:85], v[184:187], v[208:211], v[82:85]
	v_mfma_f32_16x16x32_bf16 v[70:73], v[176:179], v[216:219], v[70:73]
	v_mfma_f32_16x16x32_bf16 v[66:69], v[184:187], v[216:219], v[66:69]
	v_mfma_f32_16x16x32_bf16 v[118:121], v[180:183], v[196:199], v[118:121]
	v_mfma_f32_16x16x32_bf16 v[114:117], v[188:191], v[196:199], v[114:117]
	v_mfma_f32_16x16x32_bf16 v[102:105], v[180:183], v[204:207], v[102:105]
	v_mfma_f32_16x16x32_bf16 v[98:101], v[188:191], v[204:207], v[98:101]
	v_mfma_f32_16x16x32_bf16 v[86:89], v[180:183], v[212:215], v[86:89]
	v_mfma_f32_16x16x32_bf16 v[82:85], v[188:191], v[212:215], v[82:85]
	v_mfma_f32_16x16x32_bf16 v[70:73], v[180:183], v[220:223], v[70:73]
	v_mfma_f32_16x16x32_bf16 v[66:69], v[188:191], v[220:223], v[66:69]
	s_barrier
	s_add_i32 s20, s67, s30
	s_mov_b32 m0, s20
	ds_read_b128 v[192:195], v146 offset:49152
	ds_read_b128 v[196:199], v146 offset:50176
	ds_read_b128 v[200:203], v146 offset:51200
	ds_read_b128 v[204:207], v146 offset:52224
	ds_read_b128 v[208:211], v146 offset:53248
	ds_read_b128 v[212:215], v146 offset:54272
	ds_read_b128 v[216:219], v146 offset:55296
	ds_read_b128 v[220:223], v146 offset:56320
	global_load_lds_dwordx4 v0, s[100:101]
	s_add_i32 m0, s20, 0x2000
	s_add_i32 s20, s70, s30
	global_load_lds_dwordx4 v134, s[100:101]
	s_add_u32 s100, s100, s80
	s_addc_u32 s101, s101, 0
	s_mov_b32 m0, s20
	s_nop 0
	global_load_lds_dwordx4 v0, s[100:101]
	s_add_i32 m0, s20, 0x2000
	s_nop 0
	global_load_lds_dwordx4 v134, s[100:101]
	s_mov_b32 m0, s55
	s_nop 0
	global_load_lds_dwordx4 v130, vcc
	s_mov_b32 m0, s56
	s_nop 0
	global_load_lds_dwordx4 v132, vcc
	s_waitcnt vmcnt(8)
	s_waitcnt lgkmcnt(0)
	s_barrier
	s_waitcnt lgkmcnt(0)
	v_mfma_f32_16x16x32_bf16 v[62:65], v[160:163], v[192:195], v[62:65]
	v_mfma_f32_16x16x32_bf16 v[58:61], v[168:171], v[192:195], v[58:61]
	v_mfma_f32_16x16x32_bf16 v[46:49], v[160:163], v[200:203], v[46:49]
	v_mfma_f32_16x16x32_bf16 v[42:45], v[168:171], v[200:203], v[42:45]
	v_mfma_f32_16x16x32_bf16 v[30:33], v[160:163], v[208:211], v[30:33]
	v_mfma_f32_16x16x32_bf16 v[26:29], v[168:171], v[208:211], v[26:29]
	v_mfma_f32_16x16x32_bf16 v[14:17], v[160:163], v[216:219], v[14:17]
	v_mfma_f32_16x16x32_bf16 v[10:13], v[168:171], v[216:219], v[10:13]
	v_mfma_f32_16x16x32_bf16 v[62:65], v[164:167], v[196:199], v[62:65]
	v_mfma_f32_16x16x32_bf16 v[58:61], v[172:175], v[196:199], v[58:61]
	v_mfma_f32_16x16x32_bf16 v[46:49], v[164:167], v[204:207], v[46:49]
	v_mfma_f32_16x16x32_bf16 v[42:45], v[172:175], v[204:207], v[42:45]
	v_mfma_f32_16x16x32_bf16 v[30:33], v[164:167], v[212:215], v[30:33]
	v_mfma_f32_16x16x32_bf16 v[26:29], v[172:175], v[212:215], v[26:29]
	v_mfma_f32_16x16x32_bf16 v[14:17], v[164:167], v[220:223], v[14:17]
	v_mfma_f32_16x16x32_bf16 v[10:13], v[172:175], v[220:223], v[10:13]
	v_mfma_f32_16x16x32_bf16 v[54:57], v[176:179], v[192:195], v[54:57]
	v_mfma_f32_16x16x32_bf16 v[50:53], v[184:187], v[192:195], v[50:53]
	v_mfma_f32_16x16x32_bf16 v[38:41], v[176:179], v[200:203], v[38:41]
	v_mfma_f32_16x16x32_bf16 v[34:37], v[184:187], v[200:203], v[34:37]
	v_mfma_f32_16x16x32_bf16 v[22:25], v[176:179], v[208:211], v[22:25]
	v_mfma_f32_16x16x32_bf16 v[18:21], v[184:187], v[208:211], v[18:21]
	v_mfma_f32_16x16x32_bf16 v[6:9], v[176:179], v[216:219], v[6:9]
	v_mfma_f32_16x16x32_bf16 v[2:5], v[184:187], v[216:219], v[2:5]
	v_mfma_f32_16x16x32_bf16 v[54:57], v[180:183], v[196:199], v[54:57]
	v_mfma_f32_16x16x32_bf16 v[50:53], v[188:191], v[196:199], v[50:53]
	v_mfma_f32_16x16x32_bf16 v[38:41], v[180:183], v[204:207], v[38:41]
	v_mfma_f32_16x16x32_bf16 v[34:37], v[188:191], v[204:207], v[34:37]
	v_mfma_f32_16x16x32_bf16 v[22:25], v[180:183], v[212:215], v[22:25]
	v_mfma_f32_16x16x32_bf16 v[18:21], v[188:191], v[212:215], v[18:21]
	v_mfma_f32_16x16x32_bf16 v[6:9], v[180:183], v[220:223], v[6:9]
	v_mfma_f32_16x16x32_bf16 v[2:5], v[188:191], v[220:223], v[2:5]
	s_barrier
	s_add_u32 s16, s16, 0x100
	s_addc_u32 s17, s17, 0
	s_add_u32 s64, s64, 0x100
	s_addc_u32 s65, s65, 0
	s_cmp_ge_u32 s66, s57
	s_mov_b32 s20, s66
	s_cbranch_scc0 .LBB0_419
	s_and_b64 vcc, exec, s[10:11]
	s_cbranch_vccz .LBB0_422
	s_barrier
